# P5->P6 grid barrier also replaced by the row-panel hand-off (panel counter + grid-wide arrival counters)
# speedup vs baseline: 1.0184x; 1.0034x over previous
; template <int MODE>
; __device__ __forceinline__ void skinny(const Params& p, const h16* A, int lda, int row0, int nrt, const h16* Bt, int K, int nct) {
;     const int lane = threadIdx.x & 63, wave = threadIdx.x >> 6, fr = lane & 15, fq = lane >> 4;
;     const int gw = blockIdx.x * 8 + wave, ngw = gridDim.x * 8;
;     unsigned char* ws = p.ws;
;     for (int task = gw; task < nrt * nct; task += ngw) {
; __global__ void __launch_bounds__(512, 2) hymba_fwd(Params p) {
;     ...
;         pg8::gemm_phase(lds, g, S, E);
;         skinny<SK_UP>(p, (const h16*)(ws + OFF_X116), D, MP, MS / 16, (const h16*)(ws + OFF_WT_UP), D, DFF / 16);
.LBB0_488:
	s_cmpk_lg_i32 s33, 0x100
	s_cbranch_scc1 .Lps_b1_end
	v_cmp_eq_u32_e32 vcc, 0, v132
	s_and_saveexec_b64 s[100:101], vcc
	s_cbranch_execz .Lps_b1_x
	s_and_b32 s97, s2, 63
	s_lshl_b32 s97, s97, 6
	s_add_i32 s97, s97, 0x1b6e904
	v_mov_b32_e32 v4, s97
	v_mov_b32_e32 v5, 1
	global_atomic_add v4, v5, s[82:83]
.Lps_b1_x:
	s_or_b64 exec, exec, s[100:101]
.Lps_b1_end:
	s_movk_i32 s0, 0x800
	v_cmp_gt_i32_e32 vcc, s0, v130
	s_and_saveexec_b64 s[6:7], vcc
	s_cbranch_execz .LBB0_493
	v_mov_b32_e32 v5, 0
	v_mov_b32_e32 v141, v5
	s_mov_b64 s[8:9], 0
	s_mov_b64 s[16:17], 0x200
	v_mov_b32_e32 v10, 0x358637bd
	s_mov_b32 s18, 0x800000
	s_movk_i32 s19, 0x7ff
	v_mov_b32_e32 v11, v130

; __device__ __forceinline__ unsigned xb_ld(unsigned* p) { return __hip_atomic_load(p, __ATOMIC_RELAXED, __HIP_MEMORY_SCOPE_AGENT); }
; __device__ __forceinline__ unsigned xb_add(unsigned* p, unsigned v) { return __hip_atomic_fetch_add(p, v, __ATOMIC_RELAXED, __HIP_MEMORY_SCOPE_AGENT); }
; __device__ __forceinline__ void xcd_barrier(const XB& b) {
;     __syncthreads();
;     if (threadIdx.x == 0) {
;         unsigned* bar = b.bar;
;         __builtin_amdgcn_fence(__ATOMIC_RELEASE, "agent");
;         asm volatile("s_waitcnt vmcnt(0)" ::: "memory");
;         const unsigned old = xb_add(&bar[XB_XSUB(b.x)], 1u);
;         const unsigned gen = old / b.nloc;
;         if (old + 1u == (gen + 1u) * b.nloc) {
;             const unsigned og = xb_add(&bar[XB_TOP], 1u);
;             const unsigned target = (og / b.nx + 1u) * b.nx;
;             if (og + 1u != target) while (xb_ld(&bar[XB_TOP]) < target) __builtin_amdgcn_s_sleep(1);
;             xb_add(&bar[XB_XGEN(b.x)], 1u);
;         } else {
;             while (xb_ld(&bar[XB_XGEN(b.x)]) == gen) __builtin_amdgcn_s_sleep(1);
;         }
;         __builtin_amdgcn_fence(__ATOMIC_ACQUIRE, "agent");
;         asm volatile("s_waitcnt vmcnt(0)" ::: "memory");
;     }
;     __syncthreads();
.Linvw_1:
	s_mov_b64 s[0:1], exec
	v_readlane_b32 s6, v253, 2
	v_readlane_b32 s7, v253, 3
	s_and_b64 s[6:7], s[0:1], s[6:7]
	s_mov_b64 exec, s[6:7]
	s_cbranch_execz .LBB0_512
	s_cmpk_lg_i32 s33, 0x100
	s_cbranch_scc1 .Lps_b2_orig
	v_mov_b32_e32 v4, 0x1b71a40
	v_mov_b32_e32 v5, 1
	global_atomic_add v4, v5, s[82:83]
	s_and_b32 s97, s2, 63
	s_lshl_b32 s97, s97, 6
	s_add_i32 s97, s97, 0x1b6e904
	v_mov_b32_e32 v4, s97
	v_mov_b32_e32 v5, 0x1b71980

; __device__ __forceinline__ unsigned xb_ld(unsigned* p) { return __hip_atomic_load(p, __ATOMIC_RELAXED, __HIP_MEMORY_SCOPE_AGENT); }
; __device__ __forceinline__ unsigned xb_add(unsigned* p, unsigned v) { return __hip_atomic_fetch_add(p, v, __ATOMIC_RELAXED, __HIP_MEMORY_SCOPE_AGENT); }
; __device__ __forceinline__ void xcd_barrier(const XB& b) {
;     __syncthreads();
;     if (threadIdx.x == 0) {
;         unsigned* bar = b.bar;
;         __builtin_amdgcn_fence(__ATOMIC_RELEASE, "agent");
;         asm volatile("s_waitcnt vmcnt(0)" ::: "memory");
;         const unsigned old = xb_add(&bar[XB_XSUB(b.x)], 1u);
;         const unsigned gen = old / b.nloc;
;         if (old + 1u == (gen + 1u) * b.nloc) {
;             const unsigned og = xb_add(&bar[XB_TOP], 1u);
;             const unsigned target = (og / b.nx + 1u) * b.nx;
;             if (og + 1u != target) while (xb_ld(&bar[XB_TOP]) < target) __builtin_amdgcn_s_sleep(1);
;             xb_add(&bar[XB_XGEN(b.x)], 1u);
.Lps_b2_orig:
	s_mov_b64 s[8:9], exec
	s_nop 0
	s_waitcnt vmcnt(0)
	s_waitcnt vmcnt(0)
	s_lshl_b32 s6, s89, 8
	v_readlane_b32 s14, v253, 0
	v_mbcnt_lo_u32_b32 v0, s8, 0
	v_readlane_b32 s15, v253, 1
	s_add_u32 s6, s14, s6
	v_mbcnt_hi_u32_b32 v0, s9, v0
	s_addc_u32 s7, s15, 0
	v_cmp_eq_u32_e32 vcc, 0, v0
	s_and_saveexec_b64 s[14:15], vcc
	s_cbranch_execz .LBB0_496
	s_bcnt1_i32_b64 s8, s[8:9]
	v_mov_b32_e32 v1, 0x1000
	v_mov_b32_e32 v2, s8
	global_atomic_add v1, v1, v2, s[6:7] sc0

;     __device__ __forceinline__ void operator()(f32x4 (&acc)[2][2][4][2], const pg8::Unit& u, int wr, int wc, int fr, int fq) const {
;     ...
; #pragma unroll
;         for (int ai = 0; ai < 2; ++ai)
; #pragma unroll
;             for (int m = 0; m < 4; ++m) {
;                 const int row = row0 + ai * 128 + m * 16;
;                 const float rstd = rsqrtf(__hip_atomic_load(rowss + row, __ATOMIC_RELAXED, __HIP_MEMORY_SCOPE_AGENT) * (1.f / 1024.f) + EPS);
; #pragma unroll
;                 for (int bj = 0; bj < 2; ++bj) {
;                     const int c = col0 + bj * 128;
;                     const f32x4 w0 = *(const f32x4*)(nw + c), w1 = *(const f32x4*)(nw + c + 4);
;                     float* op = out + (size_t)row * D + c;
;                     *(f32x4*)op = acc[ai][bj][m][0] * rstd * w0; *(f32x4*)(op + 4) = acc[ai][bj][m][1] * rstd * w1;
;                 }
;             }
.LBB0_605:
	s_or_b64 exec, exec, s[4:5]
	s_barrier
	v_mov_b32_e32 v250, 0x1b71a40
	global_load_dword v251, v250, s[82:83] sc1
	v_cmp_gt_u32_e64 s[98:99], 8, v131
	v_mov_b32_e32 v240, 0xffff8010
	v_cndmask_b32_e64 v236, v240, 0, s[98:99]
	v_cndmask_b32_e64 v237, -1, 0, s[98:99]
	v_mov_b32_e32 v240, 0x8010
	v_cndmask_b32_e64 v238, 0, v240, s[98:99]
	v_mov_b32_e32 v239, 0
	global_load_dword v147, v[112:113], off sc1
	v_lshlrev_b64 v[166:167], 2, v[140:141]
	v_lshl_add_u64 v[140:141], s[60:61], 0, v[166:167]
	global_load_dwordx4 v[168:171], v[140:141], off
	global_load_dwordx4 v[172:175], v[140:141], off offset:16
	v_mov_b32_e32 v137, 0x358637bd
	s_mov_b32 s0, 0x800000
	v_lshlrev_b64 v[138:139], 12, v[138:139]
	v_lshl_add_u64 v[138:139], s[62:63], 0, v[138:139]
	v_lshl_add_u64 v[138:139], v[138:139], 0, v[166:167]
	v_lshlrev_b64 v[104:105], 12, v[104:105]
	v_lshl_add_u64 v[104:105], s[62:63], 0, v[104:105]
	v_lshl_add_u64 v[104:105], v[104:105], 0, v[166:167]
	v_lshlrev_b64 v[88:89], 12, v[88:89]
	v_lshl_add_u64 v[88:89], s[62:63], 0, v[88:89]
	v_lshl_add_u64 v[88:89], v[88:89], 0, v[166:167]
	v_lshlrev_b64 v[72:73], 12, v[72:73]
	v_lshl_add_u64 v[72:73], s[62:63], 0, v[72:73]
	v_lshl_add_u64 v[72:73], v[72:73], 0, v[166:167]
	v_lshlrev_b64 v[56:57], 12, v[56:57]
	v_lshl_add_u64 v[56:57], s[62:63], 0, v[56:57]
	v_lshl_add_u64 v[56:57], v[56:57], 0, v[166:167]
	v_lshlrev_b64 v[40:41], 12, v[40:41]
	v_lshl_add_u64 v[40:41], s[62:63], 0, v[40:41]
	v_lshl_add_u64 v[40:41], v[40:41], 0, v[166:167]
	v_lshlrev_b64 v[24:25], 12, v[24:25]
	v_lshl_add_u64 v[24:25], s[62:63], 0, v[24:25]
	v_lshl_add_u64 v[24:25], v[24:25], 0, v[166:167]
	s_waitcnt vmcnt(2)
	v_fmamk_f32 v147, v147, 0x3a800000, v137
	v_mul_f32_e32 v176, 0x4b800000, v147
	v_cmp_gt_f32_e32 vcc, s0, v147
	s_nop 1
	v_cndmask_b32_e32 v147, v147, v176, vcc
	v_rsq_f32_e32 v147, v147
	s_nop 0
	v_mul_f32_e32 v176, 0x45800000, v147
	v_cndmask_b32_e32 v176, v147, v176, vcc
	v_pk_mul_f32 v[142:143], v[142:143], v[176:177] op_sel_hi:[1,0]
	v_pk_mul_f32 v[126:127], v[126:127], v[176:177] op_sel_hi:[1,0]
	v_pk_mul_f32 v[178:179], v[124:125], v[176:177] op_sel_hi:[1,0]
	v_pk_mul_f32 v[180:181], v[122:123], v[176:177] op_sel_hi:[1,0]
	s_waitcnt vmcnt(1)
	v_pk_mul_f32 v[124:125], v[170:171], v[126:127]
	v_pk_mul_f32 v[122:123], v[168:169], v[142:143]
	s_waitcnt vmcnt(0)
	v_pk_mul_f32 v[170:171], v[174:175], v[180:181]
	v_pk_mul_f32 v[168:169], v[172:173], v[178:179]
	s_nop 1
	v_mov_b32_dpp v228, v168 row_ror:8 row_mask:0xf bank_mask:0xf
	v_mov_b32_dpp v229, v169 row_ror:8 row_mask:0xf bank_mask:0xf
	v_mov_b32_dpp v230, v170 row_ror:8 row_mask:0xf bank_mask:0xf
	v_mov_b32_dpp v231, v171 row_ror:8 row_mask:0xf bank_mask:0xf
	v_cndmask_b32_e64 v168, v228, v122, s[98:99]
	v_cndmask_b32_e64 v169, v229, v123, s[98:99]
	v_cndmask_b32_e64 v170, v230, v124, s[98:99]
	v_cndmask_b32_e64 v171, v231, v125, s[98:99]
	v_cndmask_b32_e64 v228, v122, v228, s[98:99]
	v_cndmask_b32_e64 v229, v123, v229, s[98:99]
	v_cndmask_b32_e64 v230, v124, v230, s[98:99]
	v_cndmask_b32_e64 v231, v125, v231, s[98:99]
	v_lshl_add_u64 v[232:233], v[138:139], 0, v[236:237]
	v_lshl_add_u64 v[234:235], v[138:139], 0, v[238:239]
	global_store_dwordx4 v[232:233], v[168:171], off sc0 sc1
	global_store_dwordx4 v[234:235], v[228:231], off sc0 sc1
	global_load_dwordx4 v[122:125], v[140:141], off offset:512
	s_nop 0
	global_load_dwordx4 v[168:171], v[140:141], off offset:528
	v_pk_mul_f32 v[118:119], v[118:119], v[176:177] op_sel_hi:[1,0]
	v_pk_mul_f32 v[120:121], v[120:121], v[176:177] op_sel_hi:[1,0]
	v_pk_mul_f32 v[126:127], v[114:115], v[176:177] op_sel_hi:[1,0]
	v_pk_mul_f32 v[142:143], v[116:117], v[176:177] op_sel_hi:[1,0]
	s_waitcnt vmcnt(1)
	v_pk_mul_f32 v[114:115], v[122:123], v[120:121]
	v_pk_mul_f32 v[116:117], v[124:125], v[118:119]
	s_waitcnt vmcnt(0)
	v_pk_mul_f32 v[118:119], v[168:169], v[142:143]
	v_pk_mul_f32 v[120:121], v[170:171], v[126:127]
	s_nop 1
	v_mov_b32_dpp v228, v118 row_ror:8 row_mask:0xf bank_mask:0xf
	v_mov_b32_dpp v229, v119 row_ror:8 row_mask:0xf bank_mask:0xf
	v_mov_b32_dpp v230, v120 row_ror:8 row_mask:0xf bank_mask:0xf
	v_mov_b32_dpp v231, v121 row_ror:8 row_mask:0xf bank_mask:0xf
	v_cndmask_b32_e64 v118, v228, v114, s[98:99]
	v_cndmask_b32_e64 v119, v229, v115, s[98:99]
	v_cndmask_b32_e64 v120, v230, v116, s[98:99]
	v_cndmask_b32_e64 v121, v231, v117, s[98:99]
	v_cndmask_b32_e64 v228, v114, v228, s[98:99]
	v_cndmask_b32_e64 v229, v115, v229, s[98:99]
	v_cndmask_b32_e64 v230, v116, v230, s[98:99]
	v_cndmask_b32_e64 v231, v117, v231, s[98:99]
	v_lshl_add_u64 v[232:233], v[138:139], 0, v[236:237]
	v_lshl_add_u64 v[234:235], v[138:139], 0, v[238:239]
	global_store_dwordx4 v[232:233], v[118:121], off offset:512 sc0 sc1
	global_store_dwordx4 v[234:235], v[228:231], off offset:512 sc0 sc1
	global_load_dword v122, v[152:153], off sc1
	s_nop 0
	global_load_dwordx4 v[114:117], v[140:141], off
	global_load_dwordx4 v[118:121], v[140:141], off offset:16
	s_waitcnt vmcnt(2)
	v_fmamk_f32 v122, v122, 0x3a800000, v137
	v_mul_f32_e32 v123, 0x4b800000, v122
	v_cmp_gt_f32_e32 vcc, s0, v122
	s_nop 1
	v_cndmask_b32_e32 v122, v122, v123, vcc
	v_rsq_f32_e32 v124, v122
	v_lshlrev_b64 v[122:123], 12, v[144:145]
	v_lshl_add_u64 v[122:123], s[62:63], 0, v[122:123]
	v_lshl_add_u64 v[122:123], v[122:123], 0, v[166:167]
	v_mul_f32_e32 v125, 0x45800000, v124
	v_cndmask_b32_e32 v124, v124, v125, vcc
	v_pk_mul_f32 v[126:127], v[148:149], v[124:125] op_sel_hi:[1,0]
	v_pk_mul_f32 v[110:111], v[110:111], v[124:125] op_sel_hi:[1,0]
	v_pk_mul_f32 v[138:139], v[108:109], v[124:125] op_sel_hi:[1,0]
	v_pk_mul_f32 v[142:143], v[106:107], v[124:125] op_sel_hi:[1,0]
	s_waitcnt vmcnt(1)
;     __device__ __forceinline__ void operator()(f32x4 (&acc)[2][2][4][2], const pg8::Unit& u, int wr, int wc, int fr, int fq) const {
;     ...
; #pragma unroll
;         for (int ai = 0; ai < 2; ++ai)
; #pragma unroll
;             for (int m = 0; m < 4; ++m) {
;                 const int row = row0 + ai * 128 + m * 16;
;                 const float rstd = rsqrtf(__hip_atomic_load(rowss + row, __ATOMIC_RELAXED, __HIP_MEMORY_SCOPE_AGENT) * (1.f / 1024.f) + EPS);
; #pragma unroll
;                 for (int bj = 0; bj < 2; ++bj) {
;                     const int c = col0 + bj * 128;
;                     const f32x4 w0 = *(const f32x4*)(nw + c), w1 = *(const f32x4*)(nw + c + 4);
;                     float* op = out + (size_t)row * D + c;
;                     *(f32x4*)op = acc[ai][bj][m][0] * rstd * w0; *(f32x4*)(op + 4) = acc[ai][bj][m][1] * rstd * w1;
;                 }
;             }
	v_pk_mul_f32 v[108:109], v[116:117], v[110:111]
	v_pk_mul_f32 v[106:107], v[114:115], v[126:127]
	s_waitcnt vmcnt(0)
	v_pk_mul_f32 v[116:117], v[120:121], v[142:143]
	v_pk_mul_f32 v[114:115], v[118:119], v[138:139]
	s_nop 1
	v_mov_b32_dpp v228, v114 row_ror:8 row_mask:0xf bank_mask:0xf
	v_mov_b32_dpp v229, v115 row_ror:8 row_mask:0xf bank_mask:0xf
	v_mov_b32_dpp v230, v116 row_ror:8 row_mask:0xf bank_mask:0xf
	v_mov_b32_dpp v231, v117 row_ror:8 row_mask:0xf bank_mask:0xf
	v_cndmask_b32_e64 v114, v228, v106, s[98:99]
	v_cndmask_b32_e64 v115, v229, v107, s[98:99]
	v_cndmask_b32_e64 v116, v230, v108, s[98:99]
	v_cndmask_b32_e64 v117, v231, v109, s[98:99]
	v_cndmask_b32_e64 v228, v106, v228, s[98:99]
	v_cndmask_b32_e64 v229, v107, v229, s[98:99]
	v_cndmask_b32_e64 v230, v108, v230, s[98:99]
	v_cndmask_b32_e64 v231, v109, v231, s[98:99]
	v_lshl_add_u64 v[232:233], v[122:123], 0, v[236:237]
	v_lshl_add_u64 v[234:235], v[122:123], 0, v[238:239]
	global_store_dwordx4 v[232:233], v[114:117], off sc0 sc1
	global_store_dwordx4 v[234:235], v[228:231], off sc0 sc1
	global_load_dwordx4 v[106:109], v[140:141], off offset:512
	s_nop 0
	global_load_dwordx4 v[114:117], v[140:141], off offset:528
	v_pk_mul_f32 v[102:103], v[102:103], v[124:125] op_sel_hi:[1,0]
	v_pk_mul_f32 v[100:101], v[100:101], v[124:125] op_sel_hi:[1,0]
	v_pk_mul_f32 v[110:111], v[98:99], v[124:125] op_sel_hi:[1,0]
	v_pk_mul_f32 v[118:119], v[96:97], v[124:125] op_sel_hi:[1,0]
	s_waitcnt vmcnt(1)
	v_pk_mul_f32 v[96:97], v[106:107], v[100:101]
	v_pk_mul_f32 v[98:99], v[108:109], v[102:103]
	s_waitcnt vmcnt(0)
	v_pk_mul_f32 v[100:101], v[114:115], v[118:119]
	v_pk_mul_f32 v[102:103], v[116:117], v[110:111]
	s_nop 1
	v_mov_b32_dpp v228, v100 row_ror:8 row_mask:0xf bank_mask:0xf
	v_mov_b32_dpp v229, v101 row_ror:8 row_mask:0xf bank_mask:0xf
	v_mov_b32_dpp v230, v102 row_ror:8 row_mask:0xf bank_mask:0xf
	v_mov_b32_dpp v231, v103 row_ror:8 row_mask:0xf bank_mask:0xf
	v_cndmask_b32_e64 v100, v228, v96, s[98:99]
	v_cndmask_b32_e64 v101, v229, v97, s[98:99]
	v_cndmask_b32_e64 v102, v230, v98, s[98:99]
	v_cndmask_b32_e64 v103, v231, v99, s[98:99]
	v_cndmask_b32_e64 v228, v96, v228, s[98:99]
	v_cndmask_b32_e64 v229, v97, v229, s[98:99]
	v_cndmask_b32_e64 v230, v98, v230, s[98:99]
	v_cndmask_b32_e64 v231, v99, v231, s[98:99]
	v_lshl_add_u64 v[232:233], v[122:123], 0, v[236:237]
	v_lshl_add_u64 v[234:235], v[122:123], 0, v[238:239]
	global_store_dwordx4 v[232:233], v[100:103], off offset:512 sc0 sc1
	global_store_dwordx4 v[234:235], v[228:231], off offset:512 sc0 sc1
	global_load_dword v106, v[156:157], off sc1
	s_nop 0
	global_load_dwordx4 v[96:99], v[140:141], off
	global_load_dwordx4 v[100:103], v[140:141], off offset:16
	s_waitcnt vmcnt(2)
	v_fmamk_f32 v106, v106, 0x3a800000, v137
	v_mul_f32_e32 v107, 0x4b800000, v106
	v_cmp_gt_f32_e32 vcc, s0, v106
	s_nop 1
	v_cndmask_b32_e32 v106, v106, v107, vcc
	v_rsq_f32_e32 v106, v106
	s_nop 0
	v_mul_f32_e32 v107, 0x45800000, v106
	v_cndmask_b32_e32 v106, v106, v107, vcc
	v_pk_mul_f32 v[108:109], v[150:151], v[106:107] op_sel_hi:[1,0]
	v_pk_mul_f32 v[94:95], v[94:95], v[106:107] op_sel_hi:[1,0]
	v_pk_mul_f32 v[110:111], v[92:93], v[106:107] op_sel_hi:[1,0]
	v_pk_mul_f32 v[114:115], v[90:91], v[106:107] op_sel_hi:[1,0]
	s_waitcnt vmcnt(1)
	v_pk_mul_f32 v[92:93], v[98:99], v[94:95]
	v_pk_mul_f32 v[90:91], v[96:97], v[108:109]
	s_waitcnt vmcnt(0)
	v_pk_mul_f32 v[96:97], v[102:103], v[114:115]
	v_pk_mul_f32 v[94:95], v[100:101], v[110:111]
	s_nop 1
	v_mov_b32_dpp v228, v94 row_ror:8 row_mask:0xf bank_mask:0xf
	v_mov_b32_dpp v229, v95 row_ror:8 row_mask:0xf bank_mask:0xf
	v_mov_b32_dpp v230, v96 row_ror:8 row_mask:0xf bank_mask:0xf
	v_mov_b32_dpp v231, v97 row_ror:8 row_mask:0xf bank_mask:0xf
	v_cndmask_b32_e64 v94, v228, v90, s[98:99]
	v_cndmask_b32_e64 v95, v229, v91, s[98:99]
	v_cndmask_b32_e64 v96, v230, v92, s[98:99]
	v_cndmask_b32_e64 v97, v231, v93, s[98:99]
	v_cndmask_b32_e64 v228, v90, v228, s[98:99]
	v_cndmask_b32_e64 v229, v91, v229, s[98:99]
	v_cndmask_b32_e64 v230, v92, v230, s[98:99]
	v_cndmask_b32_e64 v231, v93, v231, s[98:99]
	v_lshl_add_u64 v[232:233], v[104:105], 0, v[236:237]
	v_lshl_add_u64 v[234:235], v[104:105], 0, v[238:239]
	global_store_dwordx4 v[232:233], v[94:97], off sc0 sc1
	global_store_dwordx4 v[234:235], v[228:231], off sc0 sc1
	global_load_dwordx4 v[90:93], v[140:141], off offset:512
	s_nop 0
	global_load_dwordx4 v[94:97], v[140:141], off offset:528
	v_pk_mul_f32 v[86:87], v[86:87], v[106:107] op_sel_hi:[1,0]
	v_pk_mul_f32 v[84:85], v[84:85], v[106:107] op_sel_hi:[1,0]
	v_pk_mul_f32 v[98:99], v[82:83], v[106:107] op_sel_hi:[1,0]
	v_pk_mul_f32 v[100:101], v[80:81], v[106:107] op_sel_hi:[1,0]
	s_waitcnt vmcnt(1)
	v_pk_mul_f32 v[80:81], v[90:91], v[84:85]
	v_pk_mul_f32 v[82:83], v[92:93], v[86:87]
	s_waitcnt vmcnt(0)
	v_pk_mul_f32 v[84:85], v[94:95], v[100:101]
	v_pk_mul_f32 v[86:87], v[96:97], v[98:99]
	s_nop 1
	v_mov_b32_dpp v228, v84 row_ror:8 row_mask:0xf bank_mask:0xf
	v_mov_b32_dpp v229, v85 row_ror:8 row_mask:0xf bank_mask:0xf
	v_mov_b32_dpp v230, v86 row_ror:8 row_mask:0xf bank_mask:0xf
	v_mov_b32_dpp v231, v87 row_ror:8 row_mask:0xf bank_mask:0xf
	v_cndmask_b32_e64 v84, v228, v80, s[98:99]
	v_cndmask_b32_e64 v85, v229, v81, s[98:99]
	v_cndmask_b32_e64 v86, v230, v82, s[98:99]
	v_cndmask_b32_e64 v87, v231, v83, s[98:99]
	v_cndmask_b32_e64 v228, v80, v228, s[98:99]
	v_cndmask_b32_e64 v229, v81, v229, s[98:99]
	v_cndmask_b32_e64 v230, v82, v230, s[98:99]
	v_cndmask_b32_e64 v231, v83, v231, s[98:99]
	v_lshl_add_u64 v[232:233], v[104:105], 0, v[236:237]
	v_lshl_add_u64 v[234:235], v[104:105], 0, v[238:239]
	global_store_dwordx4 v[232:233], v[84:87], off offset:512 sc0 sc1
	global_store_dwordx4 v[234:235], v[228:231], off offset:512 sc0 sc1
	global_load_dword v90, v[160:161], off sc1
	s_nop 0
	global_load_dwordx4 v[80:83], v[140:141], off
	global_load_dwordx4 v[84:87], v[140:141], off offset:16
	s_waitcnt vmcnt(2)
;     __device__ __forceinline__ void operator()(f32x4 (&acc)[2][2][4][2], const pg8::Unit& u, int wr, int wc, int fr, int fq) const {
;     ...
; #pragma unroll
;         for (int ai = 0; ai < 2; ++ai)
; #pragma unroll
;             for (int m = 0; m < 4; ++m) {
;                 const int row = row0 + ai * 128 + m * 16;
;                 const float rstd = rsqrtf(__hip_atomic_load(rowss + row, __ATOMIC_RELAXED, __HIP_MEMORY_SCOPE_AGENT) * (1.f / 1024.f) + EPS);
; #pragma unroll
;                 for (int bj = 0; bj < 2; ++bj) {
;                     const int c = col0 + bj * 128;
;                     const f32x4 w0 = *(const f32x4*)(nw + c), w1 = *(const f32x4*)(nw + c + 4);
;                     float* op = out + (size_t)row * D + c;
;                     *(f32x4*)op = acc[ai][bj][m][0] * rstd * w0; *(f32x4*)(op + 4) = acc[ai][bj][m][1] * rstd * w1;
;                 }
;             }
	v_fmamk_f32 v90, v90, 0x3a800000, v137
	v_mul_f32_e32 v91, 0x4b800000, v90
	v_cmp_gt_f32_e32 vcc, s0, v90
	s_nop 1
	v_cndmask_b32_e32 v90, v90, v91, vcc
	v_rsq_f32_e32 v90, v90
	s_nop 0
	v_mul_f32_e32 v91, 0x45800000, v90
	v_cndmask_b32_e32 v90, v90, v91, vcc
	v_pk_mul_f32 v[92:93], v[154:155], v[90:91] op_sel_hi:[1,0]
	v_pk_mul_f32 v[78:79], v[78:79], v[90:91] op_sel_hi:[1,0]
	v_pk_mul_f32 v[94:95], v[76:77], v[90:91] op_sel_hi:[1,0]
	v_pk_mul_f32 v[96:97], v[74:75], v[90:91] op_sel_hi:[1,0]
	s_waitcnt vmcnt(1)
	v_pk_mul_f32 v[76:77], v[82:83], v[78:79]
	v_pk_mul_f32 v[74:75], v[80:81], v[92:93]
	s_waitcnt vmcnt(0)
	v_pk_mul_f32 v[80:81], v[86:87], v[96:97]
	v_pk_mul_f32 v[78:79], v[84:85], v[94:95]
	s_nop 1
	v_mov_b32_dpp v228, v78 row_ror:8 row_mask:0xf bank_mask:0xf
	v_mov_b32_dpp v229, v79 row_ror:8 row_mask:0xf bank_mask:0xf
	v_mov_b32_dpp v230, v80 row_ror:8 row_mask:0xf bank_mask:0xf
	v_mov_b32_dpp v231, v81 row_ror:8 row_mask:0xf bank_mask:0xf
	v_cndmask_b32_e64 v78, v228, v74, s[98:99]
	v_cndmask_b32_e64 v79, v229, v75, s[98:99]
	v_cndmask_b32_e64 v80, v230, v76, s[98:99]
	v_cndmask_b32_e64 v81, v231, v77, s[98:99]
	v_cndmask_b32_e64 v228, v74, v228, s[98:99]
	v_cndmask_b32_e64 v229, v75, v229, s[98:99]
	v_cndmask_b32_e64 v230, v76, v230, s[98:99]
	v_cndmask_b32_e64 v231, v77, v231, s[98:99]
	v_lshl_add_u64 v[232:233], v[88:89], 0, v[236:237]
	v_lshl_add_u64 v[234:235], v[88:89], 0, v[238:239]
	global_store_dwordx4 v[232:233], v[78:81], off sc0 sc1
	global_store_dwordx4 v[234:235], v[228:231], off sc0 sc1
	global_load_dwordx4 v[74:77], v[140:141], off offset:512
	s_nop 0
	global_load_dwordx4 v[78:81], v[140:141], off offset:528
	v_pk_mul_f32 v[70:71], v[70:71], v[90:91] op_sel_hi:[1,0]
	v_pk_mul_f32 v[68:69], v[68:69], v[90:91] op_sel_hi:[1,0]
	v_pk_mul_f32 v[82:83], v[66:67], v[90:91] op_sel_hi:[1,0]
	v_pk_mul_f32 v[84:85], v[64:65], v[90:91] op_sel_hi:[1,0]
	s_waitcnt vmcnt(1)
	v_pk_mul_f32 v[64:65], v[74:75], v[68:69]
	v_pk_mul_f32 v[66:67], v[76:77], v[70:71]
	s_waitcnt vmcnt(0)
	v_pk_mul_f32 v[68:69], v[78:79], v[84:85]
	v_pk_mul_f32 v[70:71], v[80:81], v[82:83]
	s_nop 1
	v_mov_b32_dpp v228, v68 row_ror:8 row_mask:0xf bank_mask:0xf
	v_mov_b32_dpp v229, v69 row_ror:8 row_mask:0xf bank_mask:0xf
	v_mov_b32_dpp v230, v70 row_ror:8 row_mask:0xf bank_mask:0xf
	v_mov_b32_dpp v231, v71 row_ror:8 row_mask:0xf bank_mask:0xf
	v_cndmask_b32_e64 v68, v228, v64, s[98:99]
	v_cndmask_b32_e64 v69, v229, v65, s[98:99]
	v_cndmask_b32_e64 v70, v230, v66, s[98:99]
	v_cndmask_b32_e64 v71, v231, v67, s[98:99]
	v_cndmask_b32_e64 v228, v64, v228, s[98:99]
	v_cndmask_b32_e64 v229, v65, v229, s[98:99]
	v_cndmask_b32_e64 v230, v66, v230, s[98:99]
	v_cndmask_b32_e64 v231, v67, v231, s[98:99]
	v_lshl_add_u64 v[232:233], v[88:89], 0, v[236:237]
	v_lshl_add_u64 v[234:235], v[88:89], 0, v[238:239]
	global_store_dwordx4 v[232:233], v[68:71], off offset:512 sc0 sc1
	global_store_dwordx4 v[234:235], v[228:231], off offset:512 sc0 sc1
	global_load_dword v74, v[112:113], off offset:512 sc1
	s_nop 0
	global_load_dwordx4 v[64:67], v[140:141], off
	global_load_dwordx4 v[68:71], v[140:141], off offset:16
	s_waitcnt vmcnt(2)
	v_fmamk_f32 v74, v74, 0x3a800000, v137
	v_mul_f32_e32 v75, 0x4b800000, v74
	v_cmp_gt_f32_e32 vcc, s0, v74
	s_nop 1
	v_cndmask_b32_e32 v74, v74, v75, vcc
	v_rsq_f32_e32 v74, v74
	s_nop 0
	v_mul_f32_e32 v75, 0x45800000, v74
	v_cndmask_b32_e32 v74, v74, v75, vcc
	v_pk_mul_f32 v[76:77], v[158:159], v[74:75] op_sel_hi:[1,0]
	v_pk_mul_f32 v[62:63], v[62:63], v[74:75] op_sel_hi:[1,0]
	v_pk_mul_f32 v[78:79], v[60:61], v[74:75] op_sel_hi:[1,0]
	v_pk_mul_f32 v[80:81], v[58:59], v[74:75] op_sel_hi:[1,0]
	s_waitcnt vmcnt(1)
	v_pk_mul_f32 v[60:61], v[66:67], v[62:63]
	v_pk_mul_f32 v[58:59], v[64:65], v[76:77]
	s_waitcnt vmcnt(0)
	v_pk_mul_f32 v[64:65], v[70:71], v[80:81]
	v_pk_mul_f32 v[62:63], v[68:69], v[78:79]
	s_nop 1
	v_mov_b32_dpp v228, v62 row_ror:8 row_mask:0xf bank_mask:0xf
	v_mov_b32_dpp v229, v63 row_ror:8 row_mask:0xf bank_mask:0xf
	v_mov_b32_dpp v230, v64 row_ror:8 row_mask:0xf bank_mask:0xf
	v_mov_b32_dpp v231, v65 row_ror:8 row_mask:0xf bank_mask:0xf
	v_cndmask_b32_e64 v62, v228, v58, s[98:99]
	v_cndmask_b32_e64 v63, v229, v59, s[98:99]
	v_cndmask_b32_e64 v64, v230, v60, s[98:99]
	v_cndmask_b32_e64 v65, v231, v61, s[98:99]
	v_cndmask_b32_e64 v228, v58, v228, s[98:99]
	v_cndmask_b32_e64 v229, v59, v229, s[98:99]
	v_cndmask_b32_e64 v230, v60, v230, s[98:99]
	v_cndmask_b32_e64 v231, v61, v231, s[98:99]
	v_lshl_add_u64 v[232:233], v[72:73], 0, v[236:237]
	v_lshl_add_u64 v[234:235], v[72:73], 0, v[238:239]
	global_store_dwordx4 v[232:233], v[62:65], off sc0 sc1
	global_store_dwordx4 v[234:235], v[228:231], off sc0 sc1
	global_load_dwordx4 v[58:61], v[140:141], off offset:512
	s_nop 0
	global_load_dwordx4 v[62:65], v[140:141], off offset:528
	v_pk_mul_f32 v[54:55], v[54:55], v[74:75] op_sel_hi:[1,0]
	v_pk_mul_f32 v[52:53], v[52:53], v[74:75] op_sel_hi:[1,0]
	v_pk_mul_f32 v[66:67], v[50:51], v[74:75] op_sel_hi:[1,0]
	v_pk_mul_f32 v[68:69], v[48:49], v[74:75] op_sel_hi:[1,0]
	s_waitcnt vmcnt(1)
	v_pk_mul_f32 v[48:49], v[58:59], v[52:53]
	v_pk_mul_f32 v[50:51], v[60:61], v[54:55]
	s_waitcnt vmcnt(0)
;     __device__ __forceinline__ void operator()(f32x4 (&acc)[2][2][4][2], const pg8::Unit& u, int wr, int wc, int fr, int fq) const {
;     ...
; #pragma unroll
;         for (int ai = 0; ai < 2; ++ai)
; #pragma unroll
;             for (int m = 0; m < 4; ++m) {
;                 const int row = row0 + ai * 128 + m * 16;
;                 const float rstd = rsqrtf(__hip_atomic_load(rowss + row, __ATOMIC_RELAXED, __HIP_MEMORY_SCOPE_AGENT) * (1.f / 1024.f) + EPS);
; #pragma unroll
;                 for (int bj = 0; bj < 2; ++bj) {
;                     const int c = col0 + bj * 128;
;                     const f32x4 w0 = *(const f32x4*)(nw + c), w1 = *(const f32x4*)(nw + c + 4);
;                     float* op = out + (size_t)row * D + c;
;                     *(f32x4*)op = acc[ai][bj][m][0] * rstd * w0; *(f32x4*)(op + 4) = acc[ai][bj][m][1] * rstd * w1;
;                 }
;             }
	v_pk_mul_f32 v[52:53], v[62:63], v[68:69]
	v_pk_mul_f32 v[54:55], v[64:65], v[66:67]
	s_nop 1
	v_mov_b32_dpp v228, v52 row_ror:8 row_mask:0xf bank_mask:0xf
	v_mov_b32_dpp v229, v53 row_ror:8 row_mask:0xf bank_mask:0xf
	v_mov_b32_dpp v230, v54 row_ror:8 row_mask:0xf bank_mask:0xf
	v_mov_b32_dpp v231, v55 row_ror:8 row_mask:0xf bank_mask:0xf
	v_cndmask_b32_e64 v52, v228, v48, s[98:99]
	v_cndmask_b32_e64 v53, v229, v49, s[98:99]
	v_cndmask_b32_e64 v54, v230, v50, s[98:99]
	v_cndmask_b32_e64 v55, v231, v51, s[98:99]
	v_cndmask_b32_e64 v228, v48, v228, s[98:99]
	v_cndmask_b32_e64 v229, v49, v229, s[98:99]
	v_cndmask_b32_e64 v230, v50, v230, s[98:99]
	v_cndmask_b32_e64 v231, v51, v231, s[98:99]
	v_lshl_add_u64 v[232:233], v[72:73], 0, v[236:237]
	v_lshl_add_u64 v[234:235], v[72:73], 0, v[238:239]
	global_store_dwordx4 v[232:233], v[52:55], off offset:512 sc0 sc1
	global_store_dwordx4 v[234:235], v[228:231], off offset:512 sc0 sc1
	global_load_dword v58, v[112:113], off offset:576 sc1
	s_nop 0
	global_load_dwordx4 v[48:51], v[140:141], off
	global_load_dwordx4 v[52:55], v[140:141], off offset:16
	s_waitcnt vmcnt(2)
	v_fmamk_f32 v58, v58, 0x3a800000, v137
	v_mul_f32_e32 v59, 0x4b800000, v58
	v_cmp_gt_f32_e32 vcc, s0, v58
	s_nop 1
	v_cndmask_b32_e32 v58, v58, v59, vcc
	v_rsq_f32_e32 v58, v58
	s_nop 0
	v_mul_f32_e32 v59, 0x45800000, v58
	v_cndmask_b32_e32 v58, v58, v59, vcc
	v_pk_mul_f32 v[60:61], v[162:163], v[58:59] op_sel_hi:[1,0]
	v_pk_mul_f32 v[46:47], v[46:47], v[58:59] op_sel_hi:[1,0]
	v_pk_mul_f32 v[62:63], v[44:45], v[58:59] op_sel_hi:[1,0]
	v_pk_mul_f32 v[64:65], v[42:43], v[58:59] op_sel_hi:[1,0]
	s_waitcnt vmcnt(1)
	v_pk_mul_f32 v[44:45], v[50:51], v[46:47]
	v_pk_mul_f32 v[42:43], v[48:49], v[60:61]
	s_waitcnt vmcnt(0)
	v_pk_mul_f32 v[48:49], v[54:55], v[64:65]
	v_pk_mul_f32 v[46:47], v[52:53], v[62:63]
	s_nop 1
	v_mov_b32_dpp v228, v46 row_ror:8 row_mask:0xf bank_mask:0xf
	v_mov_b32_dpp v229, v47 row_ror:8 row_mask:0xf bank_mask:0xf
	v_mov_b32_dpp v230, v48 row_ror:8 row_mask:0xf bank_mask:0xf
	v_mov_b32_dpp v231, v49 row_ror:8 row_mask:0xf bank_mask:0xf
	v_cndmask_b32_e64 v46, v228, v42, s[98:99]
	v_cndmask_b32_e64 v47, v229, v43, s[98:99]
	v_cndmask_b32_e64 v48, v230, v44, s[98:99]
	v_cndmask_b32_e64 v49, v231, v45, s[98:99]
	v_cndmask_b32_e64 v228, v42, v228, s[98:99]
	v_cndmask_b32_e64 v229, v43, v229, s[98:99]
	v_cndmask_b32_e64 v230, v44, v230, s[98:99]
	v_cndmask_b32_e64 v231, v45, v231, s[98:99]
	v_lshl_add_u64 v[232:233], v[56:57], 0, v[236:237]
	v_lshl_add_u64 v[234:235], v[56:57], 0, v[238:239]
	global_store_dwordx4 v[232:233], v[46:49], off sc0 sc1
	global_store_dwordx4 v[234:235], v[228:231], off sc0 sc1
	global_load_dwordx4 v[42:45], v[140:141], off offset:512
	s_nop 0
	global_load_dwordx4 v[46:49], v[140:141], off offset:528
	v_pk_mul_f32 v[38:39], v[38:39], v[58:59] op_sel_hi:[1,0]
	v_pk_mul_f32 v[36:37], v[36:37], v[58:59] op_sel_hi:[1,0]
	v_pk_mul_f32 v[50:51], v[34:35], v[58:59] op_sel_hi:[1,0]
	v_pk_mul_f32 v[52:53], v[32:33], v[58:59] op_sel_hi:[1,0]
	s_waitcnt vmcnt(1)
	v_pk_mul_f32 v[32:33], v[42:43], v[36:37]
	v_pk_mul_f32 v[34:35], v[44:45], v[38:39]
	s_waitcnt vmcnt(0)
	v_pk_mul_f32 v[36:37], v[46:47], v[52:53]
	v_pk_mul_f32 v[38:39], v[48:49], v[50:51]
	s_nop 1
	v_mov_b32_dpp v228, v36 row_ror:8 row_mask:0xf bank_mask:0xf
	v_mov_b32_dpp v229, v37 row_ror:8 row_mask:0xf bank_mask:0xf
	v_mov_b32_dpp v230, v38 row_ror:8 row_mask:0xf bank_mask:0xf
	v_mov_b32_dpp v231, v39 row_ror:8 row_mask:0xf bank_mask:0xf
	v_cndmask_b32_e64 v36, v228, v32, s[98:99]
	v_cndmask_b32_e64 v37, v229, v33, s[98:99]
	v_cndmask_b32_e64 v38, v230, v34, s[98:99]
	v_cndmask_b32_e64 v39, v231, v35, s[98:99]
	v_cndmask_b32_e64 v228, v32, v228, s[98:99]
	v_cndmask_b32_e64 v229, v33, v229, s[98:99]
	v_cndmask_b32_e64 v230, v34, v230, s[98:99]
	v_cndmask_b32_e64 v231, v35, v231, s[98:99]
	v_lshl_add_u64 v[232:233], v[56:57], 0, v[236:237]
	v_lshl_add_u64 v[234:235], v[56:57], 0, v[238:239]
	global_store_dwordx4 v[232:233], v[36:39], off offset:512 sc0 sc1
	global_store_dwordx4 v[234:235], v[228:231], off offset:512 sc0 sc1
	global_load_dword v42, v[112:113], off offset:640 sc1
	s_nop 0
	global_load_dwordx4 v[32:35], v[140:141], off
	global_load_dwordx4 v[36:39], v[140:141], off offset:16
	s_waitcnt vmcnt(2)
	v_fmamk_f32 v42, v42, 0x3a800000, v137
	v_mul_f32_e32 v43, 0x4b800000, v42
	v_cmp_gt_f32_e32 vcc, s0, v42
	s_nop 1
	v_cndmask_b32_e32 v42, v42, v43, vcc
	v_rsq_f32_e32 v42, v42
	s_nop 0
	v_mul_f32_e32 v43, 0x45800000, v42
	v_cndmask_b32_e32 v42, v42, v43, vcc
	v_pk_mul_f32 v[44:45], v[164:165], v[42:43] op_sel_hi:[1,0]
	v_pk_mul_f32 v[30:31], v[30:31], v[42:43] op_sel_hi:[1,0]
	v_pk_mul_f32 v[46:47], v[28:29], v[42:43] op_sel_hi:[1,0]
	v_pk_mul_f32 v[48:49], v[26:27], v[42:43] op_sel_hi:[1,0]
	s_waitcnt vmcnt(1)
	v_pk_mul_f32 v[28:29], v[34:35], v[30:31]
	v_pk_mul_f32 v[26:27], v[32:33], v[44:45]
	s_waitcnt vmcnt(0)
;     __device__ __forceinline__ void operator()(f32x4 (&acc)[2][2][4][2], const pg8::Unit& u, int wr, int wc, int fr, int fq) const {
;     ...
; #pragma unroll
;         for (int ai = 0; ai < 2; ++ai)
; #pragma unroll
;             for (int m = 0; m < 4; ++m) {
;                 const int row = row0 + ai * 128 + m * 16;
;                 const float rstd = rsqrtf(__hip_atomic_load(rowss + row, __ATOMIC_RELAXED, __HIP_MEMORY_SCOPE_AGENT) * (1.f / 1024.f) + EPS);
; #pragma unroll
;                 for (int bj = 0; bj < 2; ++bj) {
;                     const int c = col0 + bj * 128;
;                     const f32x4 w0 = *(const f32x4*)(nw + c), w1 = *(const f32x4*)(nw + c + 4);
;                     float* op = out + (size_t)row * D + c;
;                     *(f32x4*)op = acc[ai][bj][m][0] * rstd * w0; *(f32x4*)(op + 4) = acc[ai][bj][m][1] * rstd * w1;
;                 }
;             }
	v_pk_mul_f32 v[32:33], v[38:39], v[48:49]
	v_pk_mul_f32 v[30:31], v[36:37], v[46:47]
	s_nop 1
	v_mov_b32_dpp v228, v30 row_ror:8 row_mask:0xf bank_mask:0xf
	v_mov_b32_dpp v229, v31 row_ror:8 row_mask:0xf bank_mask:0xf
	v_mov_b32_dpp v230, v32 row_ror:8 row_mask:0xf bank_mask:0xf
	v_mov_b32_dpp v231, v33 row_ror:8 row_mask:0xf bank_mask:0xf
	v_cndmask_b32_e64 v30, v228, v26, s[98:99]
	v_cndmask_b32_e64 v31, v229, v27, s[98:99]
	v_cndmask_b32_e64 v32, v230, v28, s[98:99]
	v_cndmask_b32_e64 v33, v231, v29, s[98:99]
	v_cndmask_b32_e64 v228, v26, v228, s[98:99]
	v_cndmask_b32_e64 v229, v27, v229, s[98:99]
	v_cndmask_b32_e64 v230, v28, v230, s[98:99]
	v_cndmask_b32_e64 v231, v29, v231, s[98:99]
	v_lshl_add_u64 v[232:233], v[40:41], 0, v[236:237]
	v_lshl_add_u64 v[234:235], v[40:41], 0, v[238:239]
	global_store_dwordx4 v[232:233], v[30:33], off sc0 sc1
	global_store_dwordx4 v[234:235], v[228:231], off sc0 sc1
	global_load_dwordx4 v[26:29], v[140:141], off offset:512
	s_nop 0
	global_load_dwordx4 v[30:33], v[140:141], off offset:528
	v_pk_mul_f32 v[22:23], v[22:23], v[42:43] op_sel_hi:[1,0]
	v_pk_mul_f32 v[20:21], v[20:21], v[42:43] op_sel_hi:[1,0]
	v_pk_mul_f32 v[34:35], v[18:19], v[42:43] op_sel_hi:[1,0]
	v_pk_mul_f32 v[36:37], v[16:17], v[42:43] op_sel_hi:[1,0]
	s_waitcnt vmcnt(1)
	v_pk_mul_f32 v[16:17], v[26:27], v[20:21]
	v_pk_mul_f32 v[18:19], v[28:29], v[22:23]
	s_waitcnt vmcnt(0)
	v_pk_mul_f32 v[20:21], v[30:31], v[36:37]
	v_pk_mul_f32 v[22:23], v[32:33], v[34:35]
	s_nop 1
	v_mov_b32_dpp v228, v20 row_ror:8 row_mask:0xf bank_mask:0xf
	v_mov_b32_dpp v229, v21 row_ror:8 row_mask:0xf bank_mask:0xf
	v_mov_b32_dpp v230, v22 row_ror:8 row_mask:0xf bank_mask:0xf
	v_mov_b32_dpp v231, v23 row_ror:8 row_mask:0xf bank_mask:0xf
	v_cndmask_b32_e64 v20, v228, v16, s[98:99]
	v_cndmask_b32_e64 v21, v229, v17, s[98:99]
	v_cndmask_b32_e64 v22, v230, v18, s[98:99]
	v_cndmask_b32_e64 v23, v231, v19, s[98:99]
	v_cndmask_b32_e64 v228, v16, v228, s[98:99]
	v_cndmask_b32_e64 v229, v17, v229, s[98:99]
	v_cndmask_b32_e64 v230, v18, v230, s[98:99]
	v_cndmask_b32_e64 v231, v19, v231, s[98:99]
	v_lshl_add_u64 v[232:233], v[40:41], 0, v[236:237]
	v_lshl_add_u64 v[234:235], v[40:41], 0, v[238:239]
	global_store_dwordx4 v[232:233], v[20:23], off offset:512 sc0 sc1
	global_store_dwordx4 v[234:235], v[228:231], off offset:512 sc0 sc1
	global_load_dword v26, v[112:113], off offset:704 sc1
	s_nop 0
	global_load_dwordx4 v[16:19], v[140:141], off
	global_load_dwordx4 v[20:23], v[140:141], off offset:16
	s_waitcnt vmcnt(2)
	v_fmac_f32_e32 v137, 0x3a800000, v26
	v_mul_f32_e32 v26, 0x4b800000, v137
	v_cmp_gt_f32_e32 vcc, s0, v137
	s_nop 1
	v_cndmask_b32_e32 v26, v137, v26, vcc
	v_rsq_f32_e32 v26, v26
	s_nop 0
	v_mul_f32_e32 v27, 0x45800000, v26
	v_cndmask_b32_e32 v26, v26, v27, vcc
	v_pk_mul_f32 v[12:13], v[12:13], v[26:27] op_sel_hi:[1,0]
	v_pk_mul_f32 v[14:15], v[14:15], v[26:27] op_sel_hi:[1,0]
	v_pk_mul_f32 v[28:29], v[8:9], v[26:27] op_sel_hi:[1,0]
	v_pk_mul_f32 v[30:31], v[10:11], v[26:27] op_sel_hi:[1,0]
	s_waitcnt vmcnt(1)
	v_pk_mul_f32 v[10:11], v[18:19], v[14:15]
	v_pk_mul_f32 v[8:9], v[16:17], v[12:13]
	s_waitcnt vmcnt(0)
	v_pk_mul_f32 v[14:15], v[22:23], v[30:31]
	v_pk_mul_f32 v[12:13], v[20:21], v[28:29]
	s_nop 1
	v_mov_b32_dpp v228, v12 row_ror:8 row_mask:0xf bank_mask:0xf
	v_mov_b32_dpp v229, v13 row_ror:8 row_mask:0xf bank_mask:0xf
	v_mov_b32_dpp v230, v14 row_ror:8 row_mask:0xf bank_mask:0xf
	v_mov_b32_dpp v231, v15 row_ror:8 row_mask:0xf bank_mask:0xf
	v_cndmask_b32_e64 v12, v228, v8, s[98:99]
	v_cndmask_b32_e64 v13, v229, v9, s[98:99]
	v_cndmask_b32_e64 v14, v230, v10, s[98:99]
	v_cndmask_b32_e64 v15, v231, v11, s[98:99]
	v_cndmask_b32_e64 v228, v8, v228, s[98:99]
	v_cndmask_b32_e64 v229, v9, v229, s[98:99]
	v_cndmask_b32_e64 v230, v10, v230, s[98:99]
	v_cndmask_b32_e64 v231, v11, v231, s[98:99]
	v_lshl_add_u64 v[232:233], v[24:25], 0, v[236:237]
	v_lshl_add_u64 v[234:235], v[24:25], 0, v[238:239]
	global_store_dwordx4 v[232:233], v[12:15], off sc0 sc1
	global_store_dwordx4 v[234:235], v[228:231], off sc0 sc1
	global_load_dwordx4 v[8:11], v[140:141], off offset:512
	s_nop 0
	global_load_dwordx4 v[12:15], v[140:141], off offset:528
	v_pk_mul_f32 v[6:7], v[6:7], v[26:27] op_sel_hi:[1,0]
	v_pk_mul_f32 v[4:5], v[4:5], v[26:27] op_sel_hi:[1,0]
	v_pk_mul_f32 v[16:17], v[2:3], v[26:27] op_sel_hi:[1,0]
	v_pk_mul_f32 v[18:19], v[0:1], v[26:27] op_sel_hi:[1,0]
	s_waitcnt vmcnt(1)
	v_pk_mul_f32 v[0:1], v[8:9], v[4:5]
	v_pk_mul_f32 v[2:3], v[10:11], v[6:7]
	s_waitcnt vmcnt(0)
	v_pk_mul_f32 v[4:5], v[12:13], v[18:19]
	v_pk_mul_f32 v[6:7], v[14:15], v[16:17]
	s_nop 1
	v_mov_b32_dpp v228, v4 row_ror:8 row_mask:0xf bank_mask:0xf
	v_mov_b32_dpp v229, v5 row_ror:8 row_mask:0xf bank_mask:0xf
	v_mov_b32_dpp v230, v6 row_ror:8 row_mask:0xf bank_mask:0xf
	v_mov_b32_dpp v231, v7 row_ror:8 row_mask:0xf bank_mask:0xf
	v_cndmask_b32_e64 v4, v228, v0, s[98:99]
	v_cndmask_b32_e64 v5, v229, v1, s[98:99]
	v_cndmask_b32_e64 v6, v230, v2, s[98:99]
	v_cndmask_b32_e64 v7, v231, v3, s[98:99]
	v_cndmask_b32_e64 v228, v0, v228, s[98:99]
	v_cndmask_b32_e64 v229, v1, v229, s[98:99]
	v_cndmask_b32_e64 v230, v2, v230, s[98:99]
	v_cndmask_b32_e64 v231, v3, v231, s[98:99]
	v_lshl_add_u64 v[232:233], v[24:25], 0, v[236:237]
	v_lshl_add_u64 v[234:235], v[24:25], 0, v[238:239]
	global_store_dwordx4 v[232:233], v[4:7], off offset:512 sc0 sc1
	global_store_dwordx4 v[234:235], v[228:231], off offset:512 sc0 sc1

; #define LAS __attribute__((address_space(3)))
; __device__ __forceinline__ f32x4 mfma16(h16x8 a, h16x8 b, f32x4 c) { return __builtin_amdgcn_mfma_f32_16x16x32_f16(a, b, c, 0, 0, 0); }
; __device__ __forceinline__ void skinny_down_splitk(const Params& p, LAS unsigned char* lds) {
;     unsigned char* ws = p.ws;
;     LAS float* RED = (LAS float*)lds;
;     const int lane = threadIdx.x & 63, wave = threadIdx.x >> 6, fr = lane & 15, fq = lane >> 4, grp = wave >> 2, ksp = wave & 3;
;     const h16* A = (const h16*)(ws + OFF_HID16); const h16* Bt = (const h16*)(ws + OFF_WT_DN);
;     constexpr int NRT = MS / 16, NCT = D / 16;
;     for (int t0 = blockIdx.x * 2; t0 < NRT * NCT; t0 += gridDim.x * 2) {
;         const int task = t0 + grp;
;         const bool act = task < NRT * NCT;
;         const int rt = act ? task % NRT : 0, ct = act ? task / NRT : 0;
;         const h16* ap = A + (size_t)(MP + rt * 16 + fr) * DFF + ksp * 1024 + fq * 8;
;         const h16* bp = Bt + (size_t)(ct * 16 + fr) * DFF + ksp * 1024 + fq * 8;
;         f32x4 acc = {0.f, 0.f, 0.f, 0.f};
; #pragma unroll 8
;         for (int k = 0; k < 1024; k += 32) { const h16x8 a = *(const h16x8*)(ap + k); const h16x8 b = *(const h16x8*)(bp + k); acc = mfma16(b, a, acc); }
.LBB0_609:
	v_add_u32_e32 v1, s10, v14
	v_ashrrev_i32_e32 v0, 31, v1
	v_cmp_gt_i32_e64 s[0:1], s12, v1
	v_lshrrev_b32_e32 v3, 29, v0
	v_mov_b32_e32 v2, 0x4000
	s_and_saveexec_b64 s[8:9], s[0:1]
	v_add_u32_e32 v0, v1, v3
	v_and_b32_e32 v0, 0xffffff8, v0
	v_sub_u32_e32 v0, v1, v0
	v_lshl_add_u32 v2, v0, 4, v18
	s_or_b64 exec, exec, s[8:9]
	v_mov_b32_e32 v0, 0
	v_mov_b32_e32 v21, 0
	s_and_saveexec_b64 s[8:9], s[0:1]
	v_add_lshl_u32 v1, v1, v3, 1
	v_and_b32_e32 v21, -16, v1
	s_or_b64 exec, exec, s[8:9]
	v_or_b32_e32 v10, v21, v131
	v_add_u32_e32 v4, v2, v131
	v_ashrrev_i32_e32 v11, 31, v10
	v_lshlrev_b64 v[2:3], 13, v[4:5]
	v_lshlrev_b64 v[10:11], 13, v[10:11]
	v_lshl_add_u64 v[10:11], v[6:7], 0, v[10:11]
	v_lshl_add_u64 v[12:13], v[8:9], 0, v[2:3]
	s_movk_i32 s8, 0xffe0
	v_mov_b32_e32 v1, v0
	v_mov_b32_e32 v2, v0
	v_mov_b32_e32 v3, v0
.LBB0_614:
	s_cmpk_lg_i32 s33, 0x100
	s_cbranch_scc1 .Lsk6_orig
	s_waitcnt vmcnt(0)
.Lps_d_chk:
	v_readfirstlane_b32 s100, v251
	s_cmpk_lt_u32 s100, 0x100
	s_cbranch_scc0 .Lps_d_ok
	s_sleep 1
	global_load_dword v251, v250, s[82:83] sc1
	s_waitcnt vmcnt(0)
	s_branch .Lps_d_chk
; #define LAS __attribute__((address_space(3)))
; __device__ __forceinline__ f32x4 mfma16(h16x8 a, h16x8 b, f32x4 c) { return __builtin_amdgcn_mfma_f32_16x16x32_f16(a, b, c, 0, 0, 0); }
; __device__ __forceinline__ void skinny_down_splitk(const Params& p, LAS unsigned char* lds) {
;     ...
;     for (int t0 = blockIdx.x * 2; t0 < NRT * NCT; t0 += gridDim.x * 2) {
;         const int task = t0 + grp;
;         const bool act = task < NRT * NCT;
;         const int rt = act ? task % NRT : 0, ct = act ? task / NRT : 0;
;         const h16* ap = A + (size_t)(MP + rt * 16 + fr) * DFF + ksp * 1024 + fq * 8;
;         const h16* bp = Bt + (size_t)(ct * 16 + fr) * DFF + ksp * 1024 + fq * 8;
;         f32x4 acc = {0.f, 0.f, 0.f, 0.f};
; #pragma unroll 8
;         for (int k = 0; k < 1024; k += 32) { const h16x8 a = *(const h16x8*)(ap + k); const h16x8 b = *(const h16x8*)(bp + k); acc = mfma16(b, a, acc); }
;         *(LAS f32x4*)(RED + ((grp * 4 + ksp) * 64 + lane) * 4) = acc;
;         __syncthreads();
;         if (ksp == 0 && act) {
; #pragma unroll
;             for (int q = 1; q < 4; ++q) acc += *(const LAS f32x4*)(RED + ((grp * 4 + q) * 64 + lane) * 4);
.Lps_d_ok:
	v_lshrrev_b32_e32 v22, 6, v132
	v_mov_b32_e32 v140, 0
	v_readfirstlane_b32 s97, v22
	v_mov_b32_e32 v141, 0
	s_lshr_b32 s98, s97, 2
	s_and_b32 s99, s97, 3
	s_lshl_b32 s98, s98, 12
	s_lshl_b32 s99, s99, 10
	s_sub_i32 s98, s98, s99
	s_addk_i32 s98, 0xff00
	s_ashr_i32 s99, s98, 31
	v_mov_b32_e32 v22, s99
	v_add_co_u32_e64 v10, s[100:101], s98, v10
	v_mov_b32_e32 v142, 0
	v_mov_b32_e32 v143, 0
	v_addc_co_u32_e64 v11, s[100:101], v22, v11, s[100:101]
	v_add_co_u32_e64 v12, s[100:101], s98, v12
	s_mov_b32 s98, 0xfffe0000
	s_cmp_lt_u32 s97, 4
	s_cselect_b32 s98, 0x20000, s98
	v_addc_co_u32_e64 v13, s[100:101], v22, v13, s[100:101]
	s_cselect_b32 s99, 0, -1
	v_mov_b32_e32 v23, s99
	v_add_co_u32_e64 v22, s[100:101], s98, v12
	s_nop 1
	v_addc_co_u32_e64 v23, s[100:101], v23, v13, s[100:101]
	global_load_dwordx4 v[24:27], v[10:11], off
	global_load_dwordx4 v[28:31], v[12:13], off
	global_load_dwordx4 v[32:35], v[22:23], off
	global_load_dwordx4 v[36:39], v[10:11], off offset:64
	global_load_dwordx4 v[40:43], v[12:13], off offset:64
	global_load_dwordx4 v[44:47], v[22:23], off offset:64
	global_load_dwordx4 v[48:51], v[10:11], off offset:128
	global_load_dwordx4 v[52:55], v[12:13], off offset:128
	global_load_dwordx4 v[56:59], v[22:23], off offset:128
	global_load_dwordx4 v[60:63], v[10:11], off offset:192
	global_load_dwordx4 v[64:67], v[12:13], off offset:192
	global_load_dwordx4 v[68:71], v[22:23], off offset:192
	global_load_dwordx4 v[72:75], v[10:11], off offset:256
	global_load_dwordx4 v[76:79], v[12:13], off offset:256
	global_load_dwordx4 v[80:83], v[22:23], off offset:256
	global_load_dwordx4 v[84:87], v[10:11], off offset:320
	global_load_dwordx4 v[88:91], v[12:13], off offset:320
	global_load_dwordx4 v[92:95], v[22:23], off offset:320
	global_load_dwordx4 v[96:99], v[10:11], off offset:384
	global_load_dwordx4 v[100:103], v[12:13], off offset:384
	global_load_dwordx4 v[104:107], v[22:23], off offset:384
	global_load_dwordx4 v[108:111], v[10:11], off offset:448
	global_load_dwordx4 v[112:115], v[12:13], off offset:448
	global_load_dwordx4 v[116:119], v[22:23], off offset:448
	global_load_dwordx4 v[120:123], v[10:11], off offset:512
	global_load_dwordx4 v[124:127], v[12:13], off offset:512
	global_load_dwordx4 v[148:151], v[22:23], off offset:512
	global_load_dwordx4 v[152:155], v[10:11], off offset:576
	global_load_dwordx4 v[156:159], v[12:13], off offset:576
	global_load_dwordx4 v[160:163], v[22:23], off offset:576
	global_load_dwordx4 v[164:167], v[10:11], off offset:640
	global_load_dwordx4 v[168:171], v[12:13], off offset:640
	global_load_dwordx4 v[172:175], v[22:23], off offset:640
	global_load_dwordx4 v[176:179], v[10:11], off offset:704
	global_load_dwordx4 v[180:183], v[12:13], off offset:704
	global_load_dwordx4 v[184:187], v[22:23], off offset:704
	global_load_dwordx4 v[188:191], v[10:11], off offset:768
	global_load_dwordx4 v[192:195], v[12:13], off offset:768
	global_load_dwordx4 v[196:199], v[22:23], off offset:768
	global_load_dwordx4 v[200:203], v[10:11], off offset:832
	global_load_dwordx4 v[204:207], v[12:13], off offset:832
	global_load_dwordx4 v[208:211], v[22:23], off offset:832
	global_load_dwordx4 v[212:215], v[10:11], off offset:896
	global_load_dwordx4 v[216:219], v[12:13], off offset:896
	global_load_dwordx4 v[220:223], v[22:23], off offset:896
	global_load_dwordx4 v[224:227], v[10:11], off offset:960
	global_load_dwordx4 v[228:231], v[12:13], off offset:960
	global_load_dwordx4 v[232:235], v[22:23], off offset:960
	s_waitcnt vmcnt(45)
	v_mfma_f32_16x16x32_f16 v[0:3], v[24:27], v[28:31], v[0:3]
	v_mfma_f32_16x16x32_f16 v[140:143], v[24:27], v[32:35], v[140:143]
	s_waitcnt vmcnt(42)
	v_mfma_f32_16x16x32_f16 v[0:3], v[36:39], v[40:43], v[0:3]
	v_mfma_f32_16x16x32_f16 v[140:143], v[36:39], v[44:47], v[140:143]
	s_waitcnt vmcnt(39)
	v_mfma_f32_16x16x32_f16 v[0:3], v[48:51], v[52:55], v[0:3]
	v_mfma_f32_16x16x32_f16 v[140:143], v[48:51], v[56:59], v[140:143]
	s_waitcnt vmcnt(36)
	v_mfma_f32_16x16x32_f16 v[0:3], v[60:63], v[64:67], v[0:3]
	v_mfma_f32_16x16x32_f16 v[140:143], v[60:63], v[68:71], v[140:143]
	s_waitcnt vmcnt(33)
	v_mfma_f32_16x16x32_f16 v[0:3], v[72:75], v[76:79], v[0:3]
	v_mfma_f32_16x16x32_f16 v[140:143], v[72:75], v[80:83], v[140:143]
	s_waitcnt vmcnt(30)
	v_mfma_f32_16x16x32_f16 v[0:3], v[84:87], v[88:91], v[0:3]
	v_mfma_f32_16x16x32_f16 v[140:143], v[84:87], v[92:95], v[140:143]
	s_waitcnt vmcnt(27)
	v_mfma_f32_16x16x32_f16 v[0:3], v[96:99], v[100:103], v[0:3]
	v_mfma_f32_16x16x32_f16 v[140:143], v[96:99], v[104:107], v[140:143]
	s_waitcnt vmcnt(24)
	v_mfma_f32_16x16x32_f16 v[0:3], v[108:111], v[112:115], v[0:3]
	v_mfma_f32_16x16x32_f16 v[140:143], v[108:111], v[116:119], v[140:143]
	s_waitcnt vmcnt(21)
	v_mfma_f32_16x16x32_f16 v[0:3], v[120:123], v[124:127], v[0:3]
	v_mfma_f32_16x16x32_f16 v[140:143], v[120:123], v[148:151], v[140:143]
	s_waitcnt vmcnt(18)
	v_mfma_f32_16x16x32_f16 v[0:3], v[152:155], v[156:159], v[0:3]
	v_mfma_f32_16x16x32_f16 v[140:143], v[152:155], v[160:163], v[140:143]
	s_waitcnt vmcnt(15)
	v_mfma_f32_16x16x32_f16 v[0:3], v[164:167], v[168:171], v[0:3]
	v_mfma_f32_16x16x32_f16 v[140:143], v[164:167], v[172:175], v[140:143]
	s_waitcnt vmcnt(12)
	v_mfma_f32_16x16x32_f16 v[0:3], v[176:179], v[180:183], v[0:3]
	v_mfma_f32_16x16x32_f16 v[140:143], v[176:179], v[184:187], v[140:143]
	s_waitcnt vmcnt(9)
	v_mfma_f32_16x16x32_f16 v[0:3], v[188:191], v[192:195], v[0:3]
	v_mfma_f32_16x16x32_f16 v[140:143], v[188:191], v[196:199], v[140:143]
	s_waitcnt vmcnt(6)
	v_mfma_f32_16x16x32_f16 v[0:3], v[200:203], v[204:207], v[0:3]
	v_mfma_f32_16x16x32_f16 v[140:143], v[200:203], v[208:211], v[140:143]
	s_waitcnt vmcnt(3)
	v_mfma_f32_16x16x32_f16 v[0:3], v[212:215], v[216:219], v[0:3]
	v_mfma_f32_16x16x32_f16 v[140:143], v[212:215], v[220:223], v[140:143]
	s_waitcnt vmcnt(0)
	v_mfma_f32_16x16x32_f16 v[0:3], v[224:227], v[228:231], v[0:3]
	v_mfma_f32_16x16x32_f16 v[140:143], v[224:227], v[232:235], v[140:143]
	v_and_b32_e32 v24, 63, v132
	v_lshlrev_b32_e32 v24, 4, v24
	s_lshl_b32 s98, s97, 10
	s_xor_b32 s99, s98, 0x1000
	v_add_u32_e32 v25, s98, v24
	v_add_u32_e32 v24, s99, v24
	s_nop 7
	s_nop 3
	ds_write_b128 v25, v[140:143] offset:8192
	s_waitcnt lgkmcnt(0)
	s_barrier
	ds_read_b128 v[28:31], v24 offset:8192
	s_waitcnt lgkmcnt(0)
	v_pk_add_f32 v[0:1], v[0:1], v[28:29]
	v_pk_add_f32 v[2:3], v[2:3], v[30:31]
	s_branch .Lsk6_done
